# P3: the workgroup's 32 cmp tasks are also drawn from an LDS ticket counter when the interleave schedule (or row exhaustion) says one is due, so no wave is left with cmp tasks after the rows run out
# speedup vs baseline: 1.0058x; 1.0035x over previous
; __global__ void __launch_bounds__(NTHR, 2) fwd_kernel(Args a) {
;     ...
;     {
;         const int nrow = (MTOK - gw + NGW - 1) / NGW, ncmp = (8192 - gw + NGW - 1) / NGW;
;         const int stride = nrow > 0 && ncmp > 0 ? (nrow / ncmp > 0 ? nrow / ncmp : 1) : 1, phase = ((wave >> 2) * (stride >> 1) + (wave & 1)) % stride;
;         int ci = 0;
.LBB0_472:
	s_or_b64 exec, exec, s[4:5]
	s_sub_i32 s4, s20, s92
	s_add_i32 s5, s4, 0x7fff
	s_sub_i32 s7, 0xffff8001, s4
	s_ashr_i32 s6, s5, 31
	s_max_i32 s5, s5, s7
	s_mul_hi_u32 s7, s5, s73
	s_mul_i32 s8, s7, s21
	s_sub_i32 s5, s5, s8
	s_xor_b32 s6, s6, s72
	s_add_i32 s8, s7, 1
	s_sub_i32 s9, s5, s21
	s_cmp_ge_u32 s5, s21
	s_cselect_b32 s7, s8, s7
	s_cselect_b32 s5, s9, s5
	s_add_i32 s8, s7, 1
	s_cmp_ge_u32 s5, s21
	s_cselect_b32 s5, s8, s7
	s_xor_b32 s5, s5, s6
	s_sub_i32 s47, s5, s6
	s_add_i32 s5, s4, 0x1fff
	s_sub_i32 s4, 0xffffe001, s4
	s_max_i32 s4, s5, s4
	s_ashr_i32 s6, s5, 31
	s_mul_hi_u32 s5, s4, s73
	s_mul_i32 s7, s5, s21
	s_sub_i32 s4, s4, s7
	s_xor_b32 s6, s6, s72
	s_add_i32 s7, s5, 1
	s_sub_i32 s8, s4, s21
	s_cmp_ge_u32 s4, s21
	s_cselect_b32 s5, s7, s5
	s_cselect_b32 s4, s8, s4
	s_add_i32 s7, s5, 1
	s_cmp_ge_u32 s4, s21
	s_cselect_b32 s4, s7, s5
	s_xor_b32 s4, s4, s6
	s_sub_i32 s58, s4, s6
	s_cmp_gt_i32 s47, 0
	s_cselect_b64 s[8:9], -1, 0
	s_cmp_gt_i32 s58, 0
	s_cselect_b64 s[10:11], -1, 0
	s_and_b64 s[4:5], s[8:9], s[10:11]
	s_mov_b32 s69, 1
	s_and_b64 vcc, exec, s[4:5]
	v_mov_b32_e32 v1, 0
	ds_write_b32 v1, v1
	ds_write_b32 v1, v1 offset:4
	s_waitcnt lgkmcnt(0)
	s_barrier
	s_cbranch_vccz .LBB0_474
	v_cvt_f32_u32_e32 v1, s58
	s_sub_i32 s4, 0, s58
	v_rcp_iflag_f32_e32 v1, v1
	s_nop 0
	v_mul_f32_e32 v1, 0x4f7ffffe, v1
	v_cvt_u32_f32_e32 v1, v1
	s_nop 0
	v_readfirstlane_b32 s5, v1
	s_mul_i32 s4, s4, s5
	s_mul_hi_u32 s4, s5, s4
	s_add_i32 s5, s5, s4
	s_mul_hi_u32 s4, s47, s5
	s_mul_i32 s5, s4, s58
	s_sub_i32 s5, s47, s5
	s_add_i32 s6, s4, 1
	s_sub_i32 s7, s5, s58
	s_cmp_ge_u32 s5, s58
	s_cselect_b32 s4, s6, s4
	s_cselect_b32 s5, s7, s5
	s_add_i32 s6, s4, 1
	s_cmp_ge_u32 s5, s58
	s_cselect_b32 s4, s6, s4
	s_cmp_le_u32 s58, s47
	s_cselect_b32 s69, s4, 1

; #define MFMA32(a, b, c) __builtin_amdgcn_mfma_f32_32x32x16_bf16((a), (b), (c), 0, 0, 0)
; DI int crow(int r, int h) { return (r & 3) + 8 * (r >> 2) + 4 * h; }
; DI void cmp_task(const bf16_t* Z, const bf16_t* KCC, const bf16_t* VCT, bf16_t* OCMP, unsigned* selm, int b, int hk, int tg, int lane) {
;     const int r32 = lane & 31, h = lane >> 5;
;     const int tok = 8 * tg + (r32 >> 2), g = r32 & 3, head = hk * 4 + g;
;     const size_t grow = (size_t)b * SEQ + tok;
;     const bf16_t* zr = Z + grow * NZ;
;     bf16x8 qf[4];
; #pragma unroll
;     for (int s = 0; s < 4; ++s) qf[s] = *(const bf16x8*)(zr + ZC_QA + head * 64 + 16 * s + 8 * h);
;     const bf16_t* kc = KCC + (size_t)(b * 2 + hk) * 128 * 64; const bf16_t* vt = VCT + (size_t)(b * 2 + hk) * 64 * 128;
;     const int tmax = 8 * tg + 7;
;     const int nsub = tmax < 31 ? 0 : (((tmax - 31) >> 4) >> 5) + 1;
;     f32x16 p[4];
; #pragma unroll
;     for (int sub = 0; sub < 4; ++sub) {
;         if (sub < nsub) {
;             p[sub] = f16zero();
; #pragma unroll
;             for (int s = 0; s < 4; ++s) { const bf16x8 af = *(const bf16x8*)(kc + (size_t)(32 * sub + r32) * 64 + 16 * s + 8 * h); p[sub] = MFMA32(af, qf[s], p[sub]); }
; #pragma unroll
;             for (int r = 0; r < 16; ++r) { const int n = 32 * sub + crow(r, h); p[sub][r] = (16 * n + 31 <= tok) ? p[sub][r] * SM_C : NINF; }
; __global__ void __launch_bounds__(NTHR, 2) fwd_kernel(Args a) {
;     ...
;             if (ci < ncmp && (i >= nrow || (i % stride) == phase)) { const int task = gw + ci * NGW; ++ci;
;                 cmp_task(Z, KCC, VCT, OCMP, SELM, task >> 9, (task >> 8) & 1, (task + 64 * (task >> 11)) & 255, lane); }
.LBB0_481:
	s_mov_b64 s[48:49], exec
	s_mov_b64 exec, 1
	v_mov_b32_e32 v1, 4
	v_mov_b32_e32 v2, 1
	ds_add_rtn_u32 v2, v1, v2
	s_waitcnt lgkmcnt(0)
	v_readfirstlane_b32 s8, v2
	s_mov_b64 exec, s[48:49]
	s_cmpk_lt_u32 s8, 32
	s_cbranch_scc1 .Lcmp_have
	s_mov_b32 s63, s58
	s_branch .LBB0_476
.Lcmp_have:
	s_and_b32 s9, s8, 7
	s_lshr_b32 s8, s8, 3
	s_lshl_b32 s8, s8, 11
	s_add_i32 s9, s9, s8
	s_and_b32 s8, s92, -8
	s_add_i32 s9, s9, s8
	s_lshr_b32 s10, s9, 5
	s_and_b32 s10, s10, 0xc0
	s_add_i32 s10, s10, s9
	s_ashr_i32 s8, s9, 9
	s_and_b32 s54, s10, 0xff
	s_bfe_u32 s14, s9, 0x10008
	s_lshl_b32 s50, s54, 3
	s_ashr_i32 s9, s8, 31
	v_or_b32_e32 v131, s50, v113
	s_lshl_b64 s[10:11], s[8:9], 11
	v_or_b32_e32 v122, s10, v131
	v_mov_b64_e32 v[2:3], s[22:23]
	s_movk_i32 s9, 0x2200
	v_mad_u64_u32 v[2:3], s[48:49], v122, s9, v[2:3]
	v_lshl_or_b32 v1, s14, 8, v115
	v_mad_i32_i24 v3, s11, v244, v3
	v_lshlrev_b32_e32 v42, 1, v1
	v_lshl_add_u64 v[2:3], v[2:3], 0, v[42:43]
	v_mov_b32_e32 v41, v43
	v_lshl_add_u64 v[2:3], v[2:3], 0, v[40:41]
	global_load_dwordx4 v[30:33], v[2:3], off
	global_load_dwordx4 v[26:29], v[2:3], off offset:32
	global_load_dwordx4 v[22:25], v[2:3], off offset:64
	global_load_dwordx4 v[18:21], v[2:3], off offset:96
	s_lshl_b32 s8, s8, 1
	s_or_b32 s8, s8, s14
	s_ashr_i32 s9, s8, 31
	s_lshl_b64 s[8:9], s[8:9], 14
	s_or_b32 s10, s50, 7
	s_cmp_lt_u32 s10, 31
	s_cselect_b64 s[48:49], -1, 0
	s_cmp_gt_u32 s10, 30
	v_mov_b32_e32 v123, s11
	s_cselect_b64 s[10:11], -1, 0
	v_lshl_add_u64 v[124:125], v[44:45], 0, s[8:9]
	v_mov_b32_e32 v121, 0xff800000
	s_and_b64 vcc, exec, s[48:49]
	v_lshlrev_b32_e32 v126, 1, v38
	v_mov_b32_e32 v128, 0xff800000
	v_mov_b32_e32 v129, 0xff800000
	v_mov_b32_e32 v130, 0xff800000
	v_mov_b32_e32 v134, 0xff800000
	v_mov_b32_e32 v135, 0xff800000
	v_mov_b32_e32 v139, 0xff800000
	v_mov_b32_e32 v140, 0xff800000
	v_mov_b32_e32 v141, 0xff800000
	v_mov_b32_e32 v142, 0xff800000
	v_mov_b32_e32 v143, 0xff800000
	v_mov_b32_e32 v144, 0xff800000
	v_mov_b32_e32 v145, 0xff800000
	v_mov_b32_e32 v146, 0xff800000
	v_mov_b32_e32 v147, 0xff800000
	v_mov_b32_e32 v148, 0xff800000
	v_mov_b32_e32 v149, 0xff800000
	s_cbranch_vccnz .LBB0_483
	v_mov_b32_e32 v127, v43
	v_lshl_add_u64 v[94:95], v[124:125], 0, v[126:127]
	global_load_dwordx4 v[2:5], v[94:95], off
	global_load_dwordx4 v[140:143], v[94:95], off offset:32
	global_load_dwordx4 v[150:153], v[94:95], off offset:64
	global_load_dwordx4 v[154:157], v[94:95], off offset:96
	v_cmp_le_u32_e32 vcc, v46, v131
	s_waitcnt vmcnt(3)
	v_mfma_f32_32x32x16_bf16 v[2:17], v[2:5], v[30:33], 0
	s_waitcnt vmcnt(2)
	v_mfma_f32_32x32x16_bf16 v[2:17], v[140:143], v[26:29], v[2:17]
	s_waitcnt vmcnt(1)
	v_mfma_f32_32x32x16_bf16 v[2:17], v[150:153], v[22:25], v[2:17]
	s_waitcnt vmcnt(0)
	v_mfma_f32_32x32x16_bf16 v[2:17], v[154:157], v[18:21], v[2:17]
	s_nop 11
	v_pk_mul_f32 v[2:3], v[2:3], s[46:47] op_sel_hi:[1,0]
	s_nop 0
	v_cndmask_b32_e32 v128, v245, v2, vcc
	v_cmp_le_u32_e32 vcc, v37, v131
	v_mul_f32_e32 v1, 0x3e38aa3b, v4
	s_nop 0
	v_cndmask_b32_e32 v129, v245, v3, vcc
	v_cmp_le_u32_e32 vcc, v117, v131
	v_pk_mul_f32 v[2:3], v[6:7], s[46:47] op_sel_hi:[1,0]
	s_nop 0
	v_cndmask_b32_e32 v130, v245, v1, vcc
	v_mul_f32_e32 v1, 0x3e38aa3b, v5
	v_cmp_le_u32_e32 vcc, v119, v131
	s_nop 1
	v_cndmask_b32_e32 v134, v245, v1, vcc
	v_cmp_le_u32_e32 vcc, v48, v131
	v_mul_f32_e32 v1, 0x3e38aa3b, v8
	s_nop 0
	v_cndmask_b32_e32 v135, v245, v2, vcc
	v_cmp_le_u32_e32 vcc, v39, v131
	s_nop 1
	v_cndmask_b32_e32 v139, v245, v3, vcc
	v_cmp_le_u32_e32 vcc, v202, v131
	v_pk_mul_f32 v[2:3], v[10:11], s[46:47] op_sel_hi:[1,0]
	s_nop 0
	v_cndmask_b32_e32 v140, v245, v1, vcc
	v_mul_f32_e32 v1, 0x3e38aa3b, v9
	v_cmp_le_u32_e32 vcc, v203, v131
	s_nop 1
	v_cndmask_b32_e32 v141, v245, v1, vcc
	v_cmp_le_u32_e32 vcc, v50, v131
	v_mul_f32_e32 v1, 0x3e38aa3b, v12
	s_nop 0
	v_cndmask_b32_e32 v142, v245, v2, vcc
	v_cmp_le_u32_e32 vcc, v47, v131
	s_nop 1
	v_cndmask_b32_e32 v143, v245, v3, vcc
	v_cmp_le_u32_e32 vcc, v204, v131
	v_pk_mul_f32 v[2:3], v[14:15], s[46:47] op_sel_hi:[1,0]
	s_nop 0
	v_cndmask_b32_e32 v144, v245, v1, vcc
	v_mul_f32_e32 v1, 0x3e38aa3b, v13
	v_cmp_le_u32_e32 vcc, v205, v131
	s_nop 1
	v_cndmask_b32_e32 v145, v245, v1, vcc
	v_cmp_le_u32_e32 vcc, v52, v131
	v_mul_f32_e32 v1, 0x3e38aa3b, v16
	s_nop 0
	v_cndmask_b32_e32 v146, v245, v2, vcc
	v_cmp_le_u32_e32 vcc, v49, v131
	s_nop 1
	v_cndmask_b32_e32 v147, v245, v3, vcc
	v_cmp_le_u32_e32 vcc, v206, v131
	s_nop 1
	v_cndmask_b32_e32 v148, v245, v1, vcc
	v_mul_f32_e32 v1, 0x3e38aa3b, v17
	v_cmp_le_u32_e32 vcc, v207, v131
	s_nop 1
	v_cndmask_b32_e32 v149, v245, v1, vcc

; __global__ void __launch_bounds__(NTHR, 2) fwd_kernel(Args a) {
;     ...
;         for (int i = 0; i < nrow || ci < ncmp; ++i) {
;             if (ci < ncmp && (i >= nrow || (i % stride) == phase)) { const int task = gw + ci * NGW; ++ci;
;                 cmp_task(Z, KCC, VCT, OCMP, SELM, task >> 9, (task >> 8) & 1, (task + 64 * (task >> 11)) & 255, lane); }
;             if (i < nrow) { const int r = gw + i * NGW; select_row(SC, DMASK, r & 15, r >> 4, lane); }
;         }
.LBB0_534:
	s_or_b64 exec, exec, s[8:9]
	s_branch .LBB0_476
